# v112 + work queue: once a workgroup finds its preferred queue exhausted it asks the other queue first for the rest of the step (one counter round trip less per fetch)
# speedup vs baseline: 1.0010x; 1.0010x over previous
;     ...
;     auto fetch = [&]() -> int {
;         auto q1 = [&](int i) -> int { return i < N_A + N_C ? N_D + N_B + i : N_D + (i - (N_A + N_C)); };
;         if (pref == 0) { int i = (int)atomicAdd(ctr, 1u); if (i < N_D) return i; i = (int)atomicAdd(ctr + 32, 1u); return i < N_ALL - N_D ? q1(i) : N_ALL; }
;         int i = (int)atomicAdd(ctr + 32, 1u); if (i < N_ALL - N_D) return q1(i); i = (int)atomicAdd(ctr, 1u); return i < N_D ? i : N_ALL; };
.LBB0_140:
	s_or_b64 exec, exec, s[20:21]
	s_waitcnt vmcnt(0)
	v_readfirstlane_b32 s20, v2
	s_nop 1
	v_add_u32_e32 v0, s20, v0
	s_movk_i32 s20, 0x8ff
	v_cmp_lt_i32_e32 vcc, s20, v0
	s_and_saveexec_b64 s[20:21], vcc
	s_xor_b64 s[20:21], exec, s[20:21]
	s_cbranch_execz .LBB0_144
	s_mov_b32 s24, 0
	v_writelane_b32 v253, s24, 57
	v_writelane_b32 v253, s24, 58
	s_mov_b64 s[24:25], exec
	v_mbcnt_lo_u32_b32 v0, s24, 0
	v_mbcnt_hi_u32_b32 v0, s25, v0
	v_cmp_eq_u32_e32 vcc, 0, v0
	s_and_saveexec_b64 s[22:23], vcc
	s_cbranch_execz .LBB0_143
	s_bcnt1_i32_b64 s24, s[24:25]
	v_mov_b32_e32 v2, s24
	v_readlane_b32 s24, v253, 55
	v_readlane_b32 s25, v253, 56
	s_nop 4
	global_atomic_add v2, v1, v2, s[24:25] sc0

;     ...
;     auto fetch = [&]() -> int {
;         auto q1 = [&](int i) -> int { return i < N_A + N_C ? N_D + N_B + i : N_D + (i - (N_A + N_C)); };
;         if (pref == 0) { int i = (int)atomicAdd(ctr, 1u); if (i < N_D) return i; i = (int)atomicAdd(ctr + 32, 1u); return i < N_ALL - N_D ? q1(i) : N_ALL; }
;         int i = (int)atomicAdd(ctr + 32, 1u); if (i < N_ALL - N_D) return q1(i); i = (int)atomicAdd(ctr, 1u); return i < N_D ? i : N_ALL; };
.LBB0_172:
	s_or_b64 exec, exec, s[20:21]
	s_waitcnt vmcnt(0)
	v_readfirstlane_b32 s20, v2
	s_nop 1
	v_add_u32_e32 v180, s20, v0
	s_movk_i32 s20, 0xff
	v_cmp_lt_i32_e32 vcc, s20, v180
	s_and_saveexec_b64 s[20:21], vcc
	s_cbranch_execz .LBB0_176
	s_mov_b32 s24, -1
	v_writelane_b32 v253, s24, 57
	v_writelane_b32 v253, s24, 58
	s_mov_b64 s[24:25], exec
	v_mbcnt_lo_u32_b32 v0, s24, 0
	v_mbcnt_hi_u32_b32 v0, s25, v0
	v_cmp_eq_u32_e32 vcc, 0, v0
	s_and_saveexec_b64 s[22:23], vcc
	s_cbranch_execz .LBB0_175
	s_bcnt1_i32_b64 s24, s[24:25]
	v_mov_b32_e32 v2, s24
	v_readlane_b32 s24, v253, 55
	v_readlane_b32 s25, v253, 56
	s_nop 4
	global_atomic_add v2, v1, v2, s[24:25] offset:128 sc0
